# clean_k6 + static unit order as a 4-instruction bit shuffle instead of hipcc's division chain (GU1, GU2, IN unit loops)
# speedup vs baseline: 1.0004x; 1.0004x over previous
;     __host__ __device__ bool next(int i, Unit& u) const {
;         const long L = (long)i * G + c; if (L >= nwg) return false;
;         int wgid = (int)L; { const int q = nwg / NXCD, r = nwg % NXCD, xcd = wgid % NXCD, off = wgid / NXCD; wgid = (xcd < r ? xcd * (q + 1) : r * (q + 1) + (xcd - r) * q) + off; }
;         const int nig = WGM * nN, gid = wgid / nig, fm = gid * WGM, gsz = (nM - fm) < WGM ? (nM - fm) : WGM;
;         u.pm = fm + ((wgid % nig) % gsz); u.pn = (wgid % nig) / gsz; return true;
;     }
.LBB0_370:
	s_add_i32 s49, s49, 1
	s_mul_i32 s2, s49, s50
	s_mul_hi_u32 s3, s49, s34
	s_add_i32 s3, s3, s2
	s_mul_i32 s2, s49, s34
	s_add_u32 s22, s2, s38
	s_addc_u32 s23, s3, s40
	v_mov_b64_e32 v[2:3], 0xb00
	v_cmp_lt_i64_e64 s[2:3], s[22:23], v[2:3]
	v_mov_b64_e32 v[2:3], 0xaff
	v_cmp_gt_i64_e32 vcc, s[22:23], v[2:3]
	s_cbranch_vccnz .LBB0_372
	s_lshr_b32 s18, s22, 6
	s_and_b32 s5, s22, 7
	s_bfe_u32 s11, s22, 0x30003
	s_lshl3_add_u32 s20, s5, s11

;     __host__ __device__ bool next(int i, Unit& u) const {
;         const long L = (long)i * G + c; if (L >= nwg) return false;
;         int wgid = (int)L; { const int q = nwg / NXCD, r = nwg % NXCD, xcd = wgid % NXCD, off = wgid / NXCD; wgid = (xcd < r ? xcd * (q + 1) : r * (q + 1) + (xcd - r) * q) + off; }
;         const int nig = WGM * nN, gid = wgid / nig, fm = gid * WGM, gsz = (nM - fm) < WGM ? (nM - fm) : WGM;
;         u.pm = fm + ((wgid % nig) % gsz); u.pn = (wgid % nig) / gsz; return true;
;     }
.LBB0_585:
	s_add_i32 s70, s70, 1
	s_mul_i32 s2, s70, s95
	s_mul_hi_u32 s3, s70, s55
	s_add_i32 s3, s3, s2
	s_mul_i32 s2, s70, s55
	s_add_u32 s36, s2, s54
	s_addc_u32 s37, s3, s96
	v_mov_b64_e32 v[2:3], 0x480
	v_cmp_lt_i64_e64 s[2:3], s[36:37], v[2:3]
	v_mov_b64_e32 v[2:3], 0x47f
	v_cmp_gt_i64_e32 vcc, s[36:37], v[2:3]
	s_cbranch_vccnz .LBB0_587
	s_lshr_b32 s30, s36, 6
	s_and_b32 s5, s36, 7
	s_bfe_u32 s13, s36, 0x30003
	s_lshl3_add_u32 s34, s5, s13

;     __host__ __device__ bool next(int i, Unit& u) const {
;         const long L = (long)i * G + c; if (L >= nwg) return false;
;         int wgid = (int)L; { const int q = nwg / NXCD, r = nwg % NXCD, xcd = wgid % NXCD, off = wgid / NXCD; wgid = (xcd < r ? xcd * (q + 1) : r * (q + 1) + (xcd - r) * q) + off; }
;         const int nig = WGM * nN, gid = wgid / nig, fm = gid * WGM, gsz = (nM - fm) < WGM ? (nM - fm) : WGM;
;         u.pm = fm + ((wgid % nig) % gsz); u.pn = (wgid % nig) / gsz; return true;
;     }
.LBB0_1220:
	s_add_i32 s50, s50, 1
	s_mul_i32 s2, s50, s51
	s_mul_hi_u32 s3, s50, s34
	s_add_i32 s3, s3, s2
	s_mul_i32 s2, s50, s34
	s_add_u32 s22, s2, s39
	s_addc_u32 s23, s3, s41
	v_mov_b64_e32 v[2:3], 0xb00
	v_cmp_lt_i64_e64 s[2:3], s[22:23], v[2:3]
	v_mov_b64_e32 v[2:3], 0xaff
	v_cmp_gt_i64_e32 vcc, s[22:23], v[2:3]
	s_cbranch_vccnz .LBB0_1222
	s_lshr_b32 s18, s22, 6
	s_and_b32 s5, s22, 7
	s_bfe_u32 s11, s22, 0x30003
	s_lshl3_add_u32 s20, s5, s11
